# G1: accumulator zeroing moved behind the first K-step's LDS-DMA loads (mid-loop entry), so it overlaps their latency
# baseline (speedup 1.0000x reference)
; __device__ __forceinline__ int otid() { int t = threadIdx.x; asm volatile("" : "+v"(t)); return t; }
; __device__ __forceinline__ bool tile_at(int it, int MT, int NTn, int& mt, int& nt) {
;   const int G = gridDim.x;
;   const int nx = (G % 8 == 0) ? 8 : 1;
;   const int x = blockIdx.x % nx, j = blockIdx.x / nx, nloc = G / nx;
;   const int ch = x + nx * it;
;   const int q = ch * nloc + j;
;   if (q >= MT * NTn) return false;
;   const int gs = 8 * NTn;
;   const int g = q / gs, rem = q - g * gs;
;   const int gsz = min(8, MT - g * 8);
;   nt = rem / gsz;
;   mt = g * 8 + (rem - nt * gsz);
;   return true;
; }
; __device__ __forceinline__ void gemm_core_big(const bf16_t* __restrict__ A, int lda, const bf16_t* __restrict__ Bt, int ldb,
;                                               int K, f32x4 (&acc)[8][4], char* smem) {
;     ...
;   const int tid = otid(), lane = tid & 63, wave = tid >> 6;
;   const int wm = wave >> 1, wn = wave & 1;
;   const int lr = tid >> 3, lc = (tid & 7) * 8;
;   const bf16_t* ap = A + (size_t)lr * lda + lc;
;   const bf16_t* bp = Bt + (size_t)lr * ldb + lc;
;   const int nk = K >> 6;
;   const int fr = lane & 15, fq = (lane >> 4) * 8;
;   const int rswz = (fr >> 1) & 7, wswz = (lr >> 1) & 7;
;   const int fo0 = (((lane >> 4)) ^ rswz) * 8, fo1 = ((4 + (lane >> 4)) ^ rswz) * 8;
;   const bf16_t* cA = sA + (wm * 128 + fr) * LDS_STRIDE;
;   const bf16_t* cB = sB + (wn * 64 + fr) * LDS_STRIDE;
;   bf16_t* wA = sA + lr * LDS_STRIDE + (((tid & 7) ^ wswz) * 8);
;   bf16_t* wB = sB + lr * LDS_STRIDE + (((tid & 7) ^ wswz) * 8);
.LBB0_709:
	s_lshl_b32 s12, s23, s24
	s_add_i32 s12, s12, s22
	s_mul_i32 s14, s12, s16
	s_add_i32 s14, s14, s25
	s_cmpk_gt_i32 s14, 0x11c5
	s_mov_b64 s[12:13], -1
	s_cbranch_scc1 .LBB0_708
	s_mul_hi_i32 s12, s14, 0xea0ea0eb
	s_add_i32 s12, s12, s14
	s_lshr_b32 s13, s12, 31
	s_ashr_i32 s12, s12, 9
	s_add_i32 s12, s12, s13
	s_lshl_b32 s13, s12, 3
	s_sub_i32 s15, 0x41, s13
	s_min_u32 s15, s15, 8
	v_cvt_f32_ubyte0_e32 v0, s15
	v_rcp_iflag_f32_e32 v0, v0
	s_sub_i32 s26, 0, s15
	s_mulk_i32 s12, 0xfdd0
	s_add_i32 s12, s12, s14
	v_mul_f32_e32 v0, 0x4f7ffffe, v0
	v_cvt_u32_f32_e32 v0, v0
	s_abs_i32 s18, s12
	s_ashr_i32 s14, s12, 31
	v_readlane_b32 s0, v241, 11
	v_readfirstlane_b32 s27, v0
	s_mul_i32 s26, s26, s27
	s_mul_hi_u32 s26, s27, s26
	s_add_i32 s27, s27, s26
	s_mul_hi_u32 s27, s18, s27
	s_mul_i32 s26, s27, s15
	s_sub_i32 s18, s18, s26
	s_add_i32 s28, s27, 1
	s_sub_i32 s29, s18, s15
	s_cmp_ge_u32 s18, s15
	s_cselect_b32 s27, s28, s27
	s_cselect_b32 s18, s29, s18
	s_add_i32 s28, s27, 1
	s_cmp_ge_u32 s18, s15
	s_cselect_b32 s18, s28, s27
	s_xor_b32 s18, s18, s14
	s_sub_i32 s14, s18, s14
	s_add_i32 s12, s12, s13
	s_mul_i32 s13, s14, s15
	s_sub_i32 s12, s12, s13
	s_ashr_i32 s13, s12, 31
	s_lshl_b64 s[28:29], s[12:13], 19
	v_readlane_b32 s1, v241, 12
	s_add_u32 s28, s0, s28
	s_addc_u32 s29, s1, s29
	s_ashr_i32 s15, s14, 31
	v_mov_b32_e32 v8, v178
	s_lshl_b64 s[30:31], s[14:15], 18
	v_readlane_b32 s0, v244, 42
	s_add_u32 s30, s0, s30
	v_ashrrev_i32_e32 v4, 3, v8
	v_readlane_b32 s0, v244, 43
	v_ashrrev_i32_e32 v5, 31, v4
	s_addc_u32 s31, s0, s31
	v_lshlrev_b64 v[6:7], 11, v[4:5]
	v_lshlrev_b32_e32 v2, 4, v8
	v_lshrrev_b32_e32 v5, 4, v8
	v_lshl_add_u64 v[0:1], s[28:29], 0, v[6:7]
	v_and_b32_e32 v2, 0x70, v2
	v_lshl_add_u64 v[6:7], s[30:31], 0, v[6:7]
	v_xor_b32_e32 v10, v5, v8
	v_lshl_add_u64 v[0:1], v[0:1], 0, v[2:3]
	v_bfe_u32 v9, v8, 1, 3
	v_lshl_add_u64 v[132:133], v[6:7], 0, v[2:3]
	v_lshlrev_b32_e32 v2, 4, v10
	v_lshlrev_b32_e32 v7, 7, v8
	v_and_b32_e32 v2, 0x70, v2
	v_bitop3_b32 v5, v5, v9, 3 bitop3:0x6c
	v_bfe_u32 v6, v8, 4, 2
	v_and_b32_e32 v8, 0xffffc780, v7
	v_lshl_or_b32 v2, v4, 7, v2
	v_and_b32_e32 v4, 0x2780, v7
	v_lshlrev_b32_e32 v5, 4, v5
	s_waitcnt vmcnt(8)
	v_or_b32_e32 v140, v4, v5
	v_or_b32_e32 v141, v8, v5
	v_bitop3_b32 v5, v6, v9, 4 bitop3:0x36
	v_lshlrev_b32_e32 v5, 4, v5
	s_waitcnt vmcnt(4)
	v_mov_b32_e32 v28, 0
	s_mov_b32 s26, 1
	v_or_b32_e32 v142, v4, v5
	v_or_b32_e32 v143, v8, v5
	v_mov_b64_e32 v[134:135], v[0:1]
	v_mov_b64_e32 v[136:137], v[132:133]
	s_mov_b32 s0, 0x30000
	s_mov_b32 s1, 0x10000
	s_nop 0
	v_lshrrev_b32_e32 v232, 3, v178
	v_and_b32_e32 v233, 7, v178
	v_bfe_u32 v234, v178, 4, 3
	v_xor_b32_e32 v233, v233, v234
	v_lshrrev_b32_e32 v234, 6, v178
	v_lshlrev_b32_e32 v232, 11, v232
	v_lshl_add_u32 v224, v233, 4, v232
	v_add_u32_e32 v225, 0x10000, v224
	v_add_u32_e32 v226, 0x20000, v224
	v_add_u32_e32 v227, 0x30000, v224
	v_add_u32_e32 v228, 0x40000, v224
	v_add_u32_e32 v229, 0x50000, v224
	v_add_u32_e32 v230, 0x60000, v224
	v_add_u32_e32 v231, 0x70000, v224
	v_readfirstlane_b32 s15, v234
	s_lshl_b32 s15, s15, 10
	s_barrier
; __device__ __forceinline__ void gemm_core_big(const bf16_t* __restrict__ A, int lda, const bf16_t* __restrict__ Bt, int ldb,
;                                               int K, f32x4 (&acc)[8][4], char* smem) {
;     ...
;   for (int kt = 0; kt < nk; ++kt) {
;     __syncthreads();
; #pragma unroll
;     for (int i = 0; i < 8; ++i) *(u32x4*)(wA + 32 * i * LDS_STRIDE) = ra[i];
; #pragma unroll
;     for (int i = 0; i < 4; ++i) *(u32x4*)(wB + 32 * i * LDS_STRIDE) = rb[i];
;     __syncthreads();
; __device__ __forceinline__ void phase_gemm_in(const Params& p, char* smem) {
;     ...
;     f32x4 acc[8][4];
; #pragma unroll
;     for (int i = 0; i < 8; ++i)
; #pragma unroll
;       for (int j = 0; j < 4; ++j) acc[i][j] = (f32x4){0.f, 0.f, 0.f, 0.f};
;     gemm_core_big(H + (size_t)mt * 256 * 1024, 1024, W + (size_t)nt * 128 * 1024, 1024, 1024, acc, smem);
	s_add_i32 m0, s15, 0x8000
	s_nop 0
	global_load_lds_dwordx4 v224, s[30:31]
	s_mov_b32 m0, s15
	s_nop 0
	global_load_lds_dwordx4 v224, s[28:29]
	s_add_i32 m0, s15, 0x1000
	s_nop 0
	global_load_lds_dwordx4 v225, s[28:29]
	s_add_i32 m0, s15, 0x2000
	s_nop 0
	global_load_lds_dwordx4 v226, s[28:29]
	s_add_i32 m0, s15, 0x3000
	s_nop 0
	global_load_lds_dwordx4 v227, s[28:29]
	s_add_i32 m0, s15, 0x4000
	s_nop 0
	global_load_lds_dwordx4 v228, s[28:29]
	s_add_i32 m0, s15, 0x5000
	s_nop 0
	global_load_lds_dwordx4 v229, s[28:29]
	s_add_i32 m0, s15, 0x6000
	s_nop 0
	global_load_lds_dwordx4 v230, s[28:29]
	s_add_i32 m0, s15, 0x7000
	s_nop 0
	global_load_lds_dwordx4 v231, s[28:29]
	s_add_i32 m0, s15, 0x9000
	s_nop 0
	global_load_lds_dwordx4 v225, s[30:31]
	s_add_i32 m0, s15, 0xa000
	s_nop 0
	global_load_lds_dwordx4 v226, s[30:31]
	s_add_i32 m0, s15, 0xb000
	s_nop 0
	global_load_lds_dwordx4 v227, s[30:31]
	v_mov_b32_e32 v29, v28
	v_mov_b32_e32 v30, v28
	v_mov_b32_e32 v31, v28
	v_mov_b32_e32 v4, v28
	v_mov_b32_e32 v5, v28
	v_mov_b32_e32 v6, v28
	v_mov_b32_e32 v7, v28
	v_mov_b32_e32 v8, v28
	v_mov_b32_e32 v9, v28
	v_mov_b32_e32 v10, v28
	v_mov_b32_e32 v11, v28
	v_mov_b32_e32 v12, v28
	v_mov_b32_e32 v13, v28
	v_mov_b32_e32 v14, v28
	v_mov_b32_e32 v15, v28
	v_mov_b32_e32 v16, v28
	v_mov_b32_e32 v17, v28
	v_mov_b32_e32 v18, v28
	v_mov_b32_e32 v19, v28
	v_mov_b32_e32 v20, v28
	v_mov_b32_e32 v21, v28
	v_mov_b32_e32 v22, v28
	v_mov_b32_e32 v23, v28
	v_mov_b32_e32 v24, v28
	v_mov_b32_e32 v25, v28
	v_mov_b32_e32 v26, v28
	v_mov_b32_e32 v27, v28
	v_mov_b32_e32 v32, v28
	v_mov_b32_e32 v33, v28
	v_mov_b32_e32 v34, v28
	v_mov_b32_e32 v35, v28
	v_mov_b32_e32 v36, v28
	v_mov_b32_e32 v37, v28
	v_mov_b32_e32 v38, v28
	v_mov_b32_e32 v39, v28
	v_mov_b32_e32 v40, v28
	v_mov_b32_e32 v41, v28
	v_mov_b32_e32 v42, v28
	v_mov_b32_e32 v43, v28
	v_mov_b32_e32 v44, v28
	v_mov_b32_e32 v45, v28
	v_mov_b32_e32 v46, v28
	v_mov_b32_e32 v47, v28
	v_mov_b32_e32 v48, v28
	v_mov_b32_e32 v49, v28
	v_mov_b32_e32 v50, v28
	v_mov_b32_e32 v51, v28
	v_mov_b32_e32 v52, v28
	v_mov_b32_e32 v53, v28
	v_mov_b32_e32 v54, v28
	v_mov_b32_e32 v55, v28
	v_mov_b32_e32 v56, v28
	v_mov_b32_e32 v57, v28
	v_mov_b32_e32 v58, v28
	v_mov_b32_e32 v59, v28
	v_mov_b32_e32 v60, v28
	v_mov_b32_e32 v61, v28
	v_mov_b32_e32 v62, v28
	v_mov_b32_e32 v63, v28
	v_mov_b32_e32 v64, v28
	v_mov_b32_e32 v65, v28
	v_mov_b32_e32 v66, v28
	v_mov_b32_e32 v67, v28
	v_mov_b32_e32 v68, v28
	v_mov_b32_e32 v69, v28
	v_mov_b32_e32 v70, v28
	v_mov_b32_e32 v71, v28
	v_mov_b32_e32 v72, v28
	v_mov_b32_e32 v73, v28
	v_mov_b32_e32 v74, v28
	v_mov_b32_e32 v75, v28
	v_mov_b32_e32 v76, v28
	v_mov_b32_e32 v77, v28
	v_mov_b32_e32 v78, v28
	v_mov_b32_e32 v79, v28
	v_mov_b32_e32 v80, v28
	v_mov_b32_e32 v81, v28
	v_mov_b32_e32 v82, v28
	v_mov_b32_e32 v83, v28
	v_mov_b32_e32 v84, v28
	v_mov_b32_e32 v85, v28
	v_mov_b32_e32 v86, v28
	v_mov_b32_e32 v87, v28
	v_mov_b32_e32 v88, v28
	v_mov_b32_e32 v89, v28
	v_mov_b32_e32 v90, v28
	v_mov_b32_e32 v91, v28
	v_mov_b32_e32 v92, v28
	v_mov_b32_e32 v93, v28
	v_mov_b32_e32 v94, v28
	v_mov_b32_e32 v95, v28
	v_mov_b32_e32 v96, v28
	v_mov_b32_e32 v97, v28
	v_mov_b32_e32 v98, v28
	v_mov_b32_e32 v99, v28
	v_mov_b32_e32 v100, v28
	v_mov_b32_e32 v101, v28
	v_mov_b32_e32 v102, v28
	v_mov_b32_e32 v103, v28
	v_mov_b32_e32 v104, v28
	v_mov_b32_e32 v105, v28
	v_mov_b32_e32 v106, v28
	v_mov_b32_e32 v107, v28
	v_mov_b32_e32 v108, v28
	v_mov_b32_e32 v109, v28
	v_mov_b32_e32 v110, v28
	v_mov_b32_e32 v111, v28
	v_mov_b32_e32 v112, v28
	v_mov_b32_e32 v113, v28
	v_mov_b32_e32 v114, v28
	v_mov_b32_e32 v115, v28
	v_mov_b32_e32 v116, v28
	v_mov_b32_e32 v117, v28
	v_mov_b32_e32 v118, v28
	v_mov_b32_e32 v119, v28
	v_mov_b32_e32 v120, v28
	v_mov_b32_e32 v121, v28
	v_mov_b32_e32 v122, v28
	v_mov_b32_e32 v123, v28
	v_mov_b32_e32 v124, v28
	v_mov_b32_e32 v125, v28
	v_mov_b32_e32 v126, v28
	v_mov_b32_e32 v127, v28
	v_mov_b32_e32 v128, v28
	v_mov_b32_e32 v129, v28
	v_mov_b32_e32 v130, v28
	v_mov_b32_e32 v131, v28
	s_branch .Lg1_mid

; __device__ __forceinline__ void gemm_core_big(const bf16_t* __restrict__ A, int lda, const bf16_t* __restrict__ Bt, int ldb,
;                                               int K, f32x4 (&acc)[8][4], char* smem) {
;     ...
;   for (int kt = 0; kt < nk; ++kt) {
;     __syncthreads();
; #pragma unroll
;     for (int i = 0; i < 8; ++i) *(u32x4*)(wA + 32 * i * LDS_STRIDE) = ra[i];
; #pragma unroll
;     for (int i = 0; i < 4; ++i) *(u32x4*)(wB + 32 * i * LDS_STRIDE) = rb[i];
;     __syncthreads();
;     {
;       const int k1 = min(kt + 1, nk - 1) << 6;
; #pragma unroll
;       for (int i = 0; i < 8; ++i) ra[i] = *(const u32x4*)(ap + (size_t)(32 * i) * lda + k1);
; #pragma unroll
;       for (int i = 0; i < 4; ++i) rb[i] = *(const u32x4*)(bp + (size_t)(32 * i) * ldb + k1);
;     }
; #pragma unroll
;     for (int ks = 0; ks < 2; ++ks) {
;       const int fo = ks ? fo1 : fo0;
;       bf16x8 bfr[4];
; #pragma unroll
;       for (int j = 0; j < 4; ++j) bfr[j] = *(const bf16x8*)(cB + j * 16 * LDS_STRIDE + fo);
; #pragma unroll
;       for (int i = 0; i < 8; ++i) {
;         const bf16x8 af = *(const bf16x8*)(cA + i * 16 * LDS_STRIDE + fo);
; #pragma unroll
;         for (int j = 0; j < 4; ++j)
;           acc[i][j] = __builtin_amdgcn_mfma_f32_16x16x32_bf16(bfr[j], af, acc[i][j], 0, 0, 0);
;       }
;     }
.Lg1_mid:
	s_add_u32 s28, s28, 0x80
	s_addc_u32 s29, s29, 0
	s_add_u32 s30, s30, 0x80
	s_addc_u32 s31, s31, 0
	s_add_i32 s26, s26, 1
	s_lshl_b32 s18, s13, 7
	s_cmp_lg_u32 s26, 17
	s_waitcnt vmcnt(0)
	s_barrier
	ds_read_b128 v[134:137], v140 offset:32768
	ds_read_b128 v[148:151], v141 offset:0
	ds_read_b128 v[144:147], v140 offset:34816
	ds_read_b128 v[156:159], v140 offset:36864
	ds_read_b128 v[160:163], v140 offset:38912
	ds_read_b128 v[152:155], v141 offset:2048
	ds_read_b128 v[216:219], v141 offset:4096
	ds_read_b128 v[220:223], v141 offset:6144
	ds_read_b128 v[164:167], v141 offset:8192
	ds_read_b128 v[168:171], v141 offset:10240
	s_setprio 1
	s_waitcnt lgkmcnt(8)
	v_mfma_f32_16x16x32_bf16 v[128:131], v[134:137], v[148:151], v[128:131]
	s_waitcnt lgkmcnt(5)
	v_mfma_f32_16x16x32_bf16 v[124:127], v[144:147], v[148:151], v[124:127]
	v_mfma_f32_16x16x32_bf16 v[120:123], v[156:159], v[148:151], v[120:123]
	v_mfma_f32_16x16x32_bf16 v[116:119], v[160:163], v[148:151], v[116:119]
	s_waitcnt lgkmcnt(4)
	v_mfma_f32_16x16x32_bf16 v[112:115], v[134:137], v[152:155], v[112:115]
	v_mfma_f32_16x16x32_bf16 v[108:111], v[144:147], v[152:155], v[108:111]
	v_mfma_f32_16x16x32_bf16 v[104:107], v[156:159], v[152:155], v[104:107]
	v_mfma_f32_16x16x32_bf16 v[100:103], v[160:163], v[152:155], v[100:103]
	ds_read_b128 v[172:175], v141 offset:12288
	ds_read_b128 v[188:191], v141 offset:14336
	s_waitcnt lgkmcnt(4)
	v_mfma_f32_16x16x32_bf16 v[96:99], v[134:137], v[216:219], v[96:99]
	v_mfma_f32_16x16x32_bf16 v[92:95], v[144:147], v[216:219], v[92:95]
	v_mfma_f32_16x16x32_bf16 v[88:91], v[156:159], v[216:219], v[88:91]
	v_mfma_f32_16x16x32_bf16 v[84:87], v[160:163], v[216:219], v[84:87]
	v_mfma_f32_16x16x32_bf16 v[80:83], v[134:137], v[220:223], v[80:83]
	v_mfma_f32_16x16x32_bf16 v[76:79], v[144:147], v[220:223], v[76:79]
	v_mfma_f32_16x16x32_bf16 v[72:75], v[156:159], v[220:223], v[72:75]
	v_mfma_f32_16x16x32_bf16 v[68:71], v[160:163], v[220:223], v[68:71]
	ds_read_b128 v[148:151], v143 offset:0
	ds_read_b128 v[152:155], v143 offset:2048
	ds_read_b128 v[200:203], v142 offset:32768
	ds_read_b128 v[204:207], v142 offset:34816
	ds_read_b128 v[208:211], v142 offset:36864
	ds_read_b128 v[212:215], v142 offset:38912
	s_waitcnt lgkmcnt(8)
	v_mfma_f32_16x16x32_bf16 v[64:67], v[134:137], v[164:167], v[64:67]
	v_mfma_f32_16x16x32_bf16 v[60:63], v[144:147], v[164:167], v[60:63]
	v_mfma_f32_16x16x32_bf16 v[56:59], v[156:159], v[164:167], v[56:59]
	v_mfma_f32_16x16x32_bf16 v[52:55], v[160:163], v[164:167], v[52:55]
	v_mfma_f32_16x16x32_bf16 v[48:51], v[134:137], v[168:171], v[48:51]
	v_mfma_f32_16x16x32_bf16 v[44:47], v[144:147], v[168:171], v[44:47]
	v_mfma_f32_16x16x32_bf16 v[40:43], v[156:159], v[168:171], v[40:43]
	v_mfma_f32_16x16x32_bf16 v[36:39], v[160:163], v[168:171], v[36:39]
	ds_read_b128 v[216:219], v143 offset:4096
	ds_read_b128 v[220:223], v143 offset:6144
	s_waitcnt lgkmcnt(8)
	v_mfma_f32_16x16x32_bf16 v[32:35], v[134:137], v[172:175], v[32:35]
	v_mfma_f32_16x16x32_bf16 v[24:27], v[144:147], v[172:175], v[24:27]
	v_mfma_f32_16x16x32_bf16 v[20:23], v[156:159], v[172:175], v[20:23]
	v_mfma_f32_16x16x32_bf16 v[16:19], v[160:163], v[172:175], v[16:19]
	v_mfma_f32_16x16x32_bf16 v[12:15], v[134:137], v[188:191], v[12:15]
	v_mfma_f32_16x16x32_bf16 v[8:11], v[144:147], v[188:191], v[8:11]
	v_mfma_f32_16x16x32_bf16 v[4:7], v[156:159], v[188:191], v[4:7]
	v_mfma_f32_16x16x32_bf16 v[28:31], v[160:163], v[188:191], v[28:31]
	ds_read_b128 v[164:167], v143 offset:8192
	ds_read_b128 v[168:171], v143 offset:10240
	s_waitcnt lgkmcnt(4)
	v_mfma_f32_16x16x32_bf16 v[128:131], v[200:203], v[148:151], v[128:131]
	v_mfma_f32_16x16x32_bf16 v[124:127], v[204:207], v[148:151], v[124:127]
	v_mfma_f32_16x16x32_bf16 v[120:123], v[208:211], v[148:151], v[120:123]
	v_mfma_f32_16x16x32_bf16 v[116:119], v[212:215], v[148:151], v[116:119]
	v_mfma_f32_16x16x32_bf16 v[112:115], v[200:203], v[152:155], v[112:115]
	v_mfma_f32_16x16x32_bf16 v[108:111], v[204:207], v[152:155], v[108:111]
	v_mfma_f32_16x16x32_bf16 v[104:107], v[208:211], v[152:155], v[104:107]
	v_mfma_f32_16x16x32_bf16 v[100:103], v[212:215], v[152:155], v[100:103]
	ds_read_b128 v[172:175], v143 offset:12288
	ds_read_b128 v[188:191], v143 offset:14336
	s_waitcnt lgkmcnt(4)
	v_mfma_f32_16x16x32_bf16 v[96:99], v[200:203], v[216:219], v[96:99]
	v_mfma_f32_16x16x32_bf16 v[92:95], v[204:207], v[216:219], v[92:95]
	v_mfma_f32_16x16x32_bf16 v[88:91], v[208:211], v[216:219], v[88:91]
	v_mfma_f32_16x16x32_bf16 v[84:87], v[212:215], v[216:219], v[84:87]
	v_mfma_f32_16x16x32_bf16 v[80:83], v[200:203], v[220:223], v[80:83]
	v_mfma_f32_16x16x32_bf16 v[76:79], v[204:207], v[220:223], v[76:79]
	v_mfma_f32_16x16x32_bf16 v[72:75], v[208:211], v[220:223], v[72:75]
	v_mfma_f32_16x16x32_bf16 v[68:71], v[212:215], v[220:223], v[68:71]
	s_waitcnt lgkmcnt(2)
	v_mfma_f32_16x16x32_bf16 v[64:67], v[200:203], v[164:167], v[64:67]
	v_mfma_f32_16x16x32_bf16 v[60:63], v[204:207], v[164:167], v[60:63]
	v_mfma_f32_16x16x32_bf16 v[56:59], v[208:211], v[164:167], v[56:59]
	v_mfma_f32_16x16x32_bf16 v[52:55], v[212:215], v[164:167], v[52:55]
	v_mfma_f32_16x16x32_bf16 v[48:51], v[200:203], v[168:171], v[48:51]
	v_mfma_f32_16x16x32_bf16 v[44:47], v[204:207], v[168:171], v[44:47]
	v_mfma_f32_16x16x32_bf16 v[40:43], v[208:211], v[168:171], v[40:43]
	v_mfma_f32_16x16x32_bf16 v[36:39], v[212:215], v[168:171], v[36:39]
	s_waitcnt lgkmcnt(0)
	v_mfma_f32_16x16x32_bf16 v[32:35], v[200:203], v[172:175], v[32:35]
	v_mfma_f32_16x16x32_bf16 v[24:27], v[204:207], v[172:175], v[24:27]
	v_mfma_f32_16x16x32_bf16 v[20:23], v[208:211], v[172:175], v[20:23]
	v_mfma_f32_16x16x32_bf16 v[16:19], v[212:215], v[172:175], v[16:19]
	v_mfma_f32_16x16x32_bf16 v[12:15], v[200:203], v[188:191], v[12:15]
	v_mfma_f32_16x16x32_bf16 v[8:11], v[204:207], v[188:191], v[8:11]
	v_mfma_f32_16x16x32_bf16 v[4:7], v[208:211], v[188:191], v[4:7]
	v_mfma_f32_16x16x32_bf16 v[28:31], v[212:215], v[188:191], v[28:31]
	s_cbranch_scc1 .LBB0_711
; __device__ __forceinline__ unsigned pack2(float a, float b) { return (unsigned)f2bf(a) | ((unsigned)f2bf(b) << 16); }
; __device__ __forceinline__ void phase_gemm_in(const Params& p, char* smem) {
;     ...
;     bf16_t* dst; int ldd, ncol0;
;     if (nt < PRE_W / 128) { dst = PRE; ldd = PRE_W; ncol0 = nt * 128; }
;     else { dst = POST; ldd = POST_W; ncol0 = (nt - PRE_W / 128) * 128; }
; #pragma unroll
;     for (int i = 0; i < 8; ++i) {
;       const int m = mt * 256 + wm * 128 + i * 16 + (lane & 15);
; #pragma unroll
;       for (int j = 0; j < 4; ++j) {
;         const int n = ncol0 + wn * 64 + j * 16 + (lane >> 4) * 4;
;         uint2 o;
;         o.x = pack2(acc[i][j][0], acc[i][j][1]);
;         o.y = pack2(acc[i][j][2], acc[i][j][3]);
;         *(uint2*)(dst + (size_t)m * ldd + n) = o;
;       }
;     }
	s_setprio 0
	s_lshl_b32 s13, s14, 7
	s_add_i32 s15, s13, 0xffffef00
	s_cmp_lt_i32 s14, 34
	s_mov_b32 s14, 0x4100000
	s_cselect_b32 s18, s14, 0xcb20000
	s_movk_i32 s0, 0x1200
	s_cselect_b32 s15, s13, s15
	s_cselect_b32 s14, 0x1100, s0
	v_lshl_add_u32 v2, s12, 8, v138
	s_add_u32 s12, s10, s18
	v_or_b32_e32 v0, s15, v139
	s_addc_u32 s13, s11, 0
	s_lshl_b32 s18, s14, 4
	v_ashrrev_i32_e32 v1, 31, v0
	v_lshlrev_b64 v[0:1], 1, v[0:1]
	v_bfe_u32 v136, v178, 4, 1
	v_mul_u32_u24_e32 v136, 24, v136
	v_add_u32_e32 v0, v0, v136
	v_bfe_u32 v136, v178, 3, 1
	v_lshlrev_b32_e32 v136, 6, v136
	v_add_u32_e32 v0, v0, v136
	v_and_b32_e32 v2, 0xfffffff7, v2
	v_mad_i64_i32 v[132:133], s[26:27], s14, v2, 0
	v_lshl_add_u64 v[132:133], v[132:133], 1, s[12:13]
	v_lshl_add_u64 v[132:133], v[132:133], 0, v[0:1]
	v_lshl_add_u64 v[134:135], v[132:133], 0, s[18:19]
	v_cvt_pk_bf16_f32 v144, v128, v129
	v_cvt_pk_bf16_f32 v146, v124, v125
	v_cvt_pk_bf16_f32 v145, v130, v131
	v_cvt_pk_bf16_f32 v147, v126, v127
	v_cvt_pk_bf16_f32 v148, v120, v121
	v_cvt_pk_bf16_f32 v150, v116, v117
	v_cvt_pk_bf16_f32 v149, v122, v123
	v_cvt_pk_bf16_f32 v151, v118, v119
	v_permlane16_swap_b32_e32 v144, v146
	v_permlane16_swap_b32_e32 v145, v147
	v_permlane16_swap_b32_e32 v148, v150
	v_permlane16_swap_b32_e32 v149, v151
	v_mov_b32_e32 v152, v144
	v_mov_b32_e32 v153, v145
	v_mov_b32_e32 v154, v146
	v_mov_b32_e32 v155, v147
	v_mov_b32_dpp v144, v148 row_ror:8 row_mask:0xf bank_mask:0xc
	v_mov_b32_dpp v145, v149 row_ror:8 row_mask:0xf bank_mask:0xc
	v_mov_b32_dpp v146, v150 row_ror:8 row_mask:0xf bank_mask:0xc
	v_mov_b32_dpp v147, v151 row_ror:8 row_mask:0xf bank_mask:0xc
	v_mov_b32_dpp v148, v152 row_ror:8 row_mask:0xf bank_mask:0x3
	v_mov_b32_dpp v149, v153 row_ror:8 row_mask:0xf bank_mask:0x3
	v_mov_b32_dpp v150, v154 row_ror:8 row_mask:0xf bank_mask:0x3
	v_mov_b32_dpp v151, v155 row_ror:8 row_mask:0xf bank_mask:0x3
	global_store_dwordx4 v[132:133], v[144:147], off nt
	global_store_dwordx4 v[134:135], v[148:151], off nt
	v_or_b32_e32 v172, 0x10, v2
	v_mad_i64_i32 v[168:169], s[26:27], s14, v172, 0
	v_lshl_add_u64 v[168:169], v[168:169], 1, s[12:13]
	v_lshl_add_u64 v[168:169], v[168:169], 0, v[0:1]
	v_lshl_add_u64 v[170:171], v[168:169], 0, s[18:19]
	v_cvt_pk_bf16_f32 v156, v112, v113
	v_cvt_pk_bf16_f32 v158, v108, v109
	v_cvt_pk_bf16_f32 v157, v114, v115
	v_cvt_pk_bf16_f32 v159, v110, v111
	v_cvt_pk_bf16_f32 v160, v104, v105
	v_cvt_pk_bf16_f32 v162, v100, v101
	v_cvt_pk_bf16_f32 v161, v106, v107
	v_cvt_pk_bf16_f32 v163, v102, v103
	v_permlane16_swap_b32_e32 v156, v158
	v_permlane16_swap_b32_e32 v157, v159
	v_permlane16_swap_b32_e32 v160, v162
	v_permlane16_swap_b32_e32 v161, v163
	v_mov_b32_e32 v164, v156
	v_mov_b32_e32 v165, v157
	v_mov_b32_e32 v166, v158
	v_mov_b32_e32 v167, v159
	v_mov_b32_dpp v156, v160 row_ror:8 row_mask:0xf bank_mask:0xc
	v_mov_b32_dpp v157, v161 row_ror:8 row_mask:0xf bank_mask:0xc
	v_mov_b32_dpp v158, v162 row_ror:8 row_mask:0xf bank_mask:0xc
	v_mov_b32_dpp v159, v163 row_ror:8 row_mask:0xf bank_mask:0xc
	v_mov_b32_dpp v160, v164 row_ror:8 row_mask:0xf bank_mask:0x3
	v_mov_b32_dpp v161, v165 row_ror:8 row_mask:0xf bank_mask:0x3
	v_mov_b32_dpp v162, v166 row_ror:8 row_mask:0xf bank_mask:0x3
	v_mov_b32_dpp v163, v167 row_ror:8 row_mask:0xf bank_mask:0x3
	global_store_dwordx4 v[168:169], v[156:159], off nt
	global_store_dwordx4 v[170:171], v[160:163], off nt
	v_or_b32_e32 v172, 0x20, v2
	v_mad_i64_i32 v[132:133], s[26:27], s14, v172, 0
	v_lshl_add_u64 v[132:133], v[132:133], 1, s[12:13]
	v_lshl_add_u64 v[132:133], v[132:133], 0, v[0:1]
	v_lshl_add_u64 v[134:135], v[132:133], 0, s[18:19]
	v_cvt_pk_bf16_f32 v144, v96, v97
	v_cvt_pk_bf16_f32 v146, v92, v93
	v_cvt_pk_bf16_f32 v145, v98, v99
	v_cvt_pk_bf16_f32 v147, v94, v95
	v_cvt_pk_bf16_f32 v148, v88, v89
	v_cvt_pk_bf16_f32 v150, v84, v85
	v_cvt_pk_bf16_f32 v149, v90, v91
	v_cvt_pk_bf16_f32 v151, v86, v87
	v_permlane16_swap_b32_e32 v144, v146
	v_permlane16_swap_b32_e32 v145, v147
	v_permlane16_swap_b32_e32 v148, v150
	v_permlane16_swap_b32_e32 v149, v151
	v_mov_b32_e32 v152, v144
	v_mov_b32_e32 v153, v145
	v_mov_b32_e32 v154, v146
	v_mov_b32_e32 v155, v147
	v_mov_b32_dpp v144, v148 row_ror:8 row_mask:0xf bank_mask:0xc
	v_mov_b32_dpp v145, v149 row_ror:8 row_mask:0xf bank_mask:0xc
	v_mov_b32_dpp v146, v150 row_ror:8 row_mask:0xf bank_mask:0xc
	v_mov_b32_dpp v147, v151 row_ror:8 row_mask:0xf bank_mask:0xc
	v_mov_b32_dpp v148, v152 row_ror:8 row_mask:0xf bank_mask:0x3
	v_mov_b32_dpp v149, v153 row_ror:8 row_mask:0xf bank_mask:0x3
	v_mov_b32_dpp v150, v154 row_ror:8 row_mask:0xf bank_mask:0x3
	v_mov_b32_dpp v151, v155 row_ror:8 row_mask:0xf bank_mask:0x3
	global_store_dwordx4 v[132:133], v[144:147], off nt
	global_store_dwordx4 v[134:135], v[148:151], off nt
	v_or_b32_e32 v172, 0x30, v2
	v_mad_i64_i32 v[168:169], s[26:27], s14, v172, 0
	v_lshl_add_u64 v[168:169], v[168:169], 1, s[12:13]
	v_lshl_add_u64 v[168:169], v[168:169], 0, v[0:1]
	v_lshl_add_u64 v[170:171], v[168:169], 0, s[18:19]
	v_cvt_pk_bf16_f32 v156, v80, v81
	v_cvt_pk_bf16_f32 v158, v76, v77
	v_cvt_pk_bf16_f32 v157, v82, v83
	v_cvt_pk_bf16_f32 v159, v78, v79
	v_cvt_pk_bf16_f32 v160, v72, v73
	v_cvt_pk_bf16_f32 v162, v68, v69
	v_cvt_pk_bf16_f32 v161, v74, v75
	v_cvt_pk_bf16_f32 v163, v70, v71
	v_permlane16_swap_b32_e32 v156, v158
	v_permlane16_swap_b32_e32 v157, v159
	v_permlane16_swap_b32_e32 v160, v162
	v_permlane16_swap_b32_e32 v161, v163
	v_mov_b32_e32 v164, v156
	v_mov_b32_e32 v165, v157
	v_mov_b32_e32 v166, v158
	v_mov_b32_e32 v167, v159
	v_mov_b32_dpp v156, v160 row_ror:8 row_mask:0xf bank_mask:0xc
	v_mov_b32_dpp v157, v161 row_ror:8 row_mask:0xf bank_mask:0xc
; __device__ __forceinline__ unsigned pack2(float a, float b) { return (unsigned)f2bf(a) | ((unsigned)f2bf(b) << 16); }
; __device__ __forceinline__ void phase_gemm_in(const Params& p, char* smem) {
;     ...
;   for (int it = 0; it < iters; ++it) {
;     int mt, nt;
;     if (!tile_at(it, MT, NTn, mt, nt)) break;
;     f32x4 acc[8][4];
; #pragma unroll
;     for (int i = 0; i < 8; ++i)
; #pragma unroll
;       for (int j = 0; j < 4; ++j) acc[i][j] = (f32x4){0.f, 0.f, 0.f, 0.f};
;     gemm_core_big(H + (size_t)mt * 256 * 1024, 1024, W + (size_t)nt * 128 * 1024, 1024, 1024, acc, smem);
;     bf16_t* dst; int ldd, ncol0;
;     if (nt < PRE_W / 128) { dst = PRE; ldd = PRE_W; ncol0 = nt * 128; }
;     else { dst = POST; ldd = POST_W; ncol0 = (nt - PRE_W / 128) * 128; }
; #pragma unroll
;     for (int i = 0; i < 8; ++i) {
;       const int m = mt * 256 + wm * 128 + i * 16 + (lane & 15);
; #pragma unroll
;       for (int j = 0; j < 4; ++j) {
;         const int n = ncol0 + wn * 64 + j * 16 + (lane >> 4) * 4;
;         uint2 o;
;         o.x = pack2(acc[i][j][0], acc[i][j][1]);
;         o.y = pack2(acc[i][j][2], acc[i][j][3]);
;         *(uint2*)(dst + (size_t)m * ldd + n) = o;
;       }
;     }
	v_mov_b32_dpp v158, v162 row_ror:8 row_mask:0xf bank_mask:0xc
	v_mov_b32_dpp v159, v163 row_ror:8 row_mask:0xf bank_mask:0xc
	v_mov_b32_dpp v160, v164 row_ror:8 row_mask:0xf bank_mask:0x3
	v_mov_b32_dpp v161, v165 row_ror:8 row_mask:0xf bank_mask:0x3
	v_mov_b32_dpp v162, v166 row_ror:8 row_mask:0xf bank_mask:0x3
	v_mov_b32_dpp v163, v167 row_ror:8 row_mask:0xf bank_mask:0x3
	global_store_dwordx4 v[168:169], v[156:159], off nt
	global_store_dwordx4 v[170:171], v[160:163], off nt
	v_or_b32_e32 v172, 0x40, v2
	v_mad_i64_i32 v[132:133], s[26:27], s14, v172, 0
	v_lshl_add_u64 v[132:133], v[132:133], 1, s[12:13]
	v_lshl_add_u64 v[132:133], v[132:133], 0, v[0:1]
	v_lshl_add_u64 v[134:135], v[132:133], 0, s[18:19]
	v_cvt_pk_bf16_f32 v144, v64, v65
	v_cvt_pk_bf16_f32 v146, v60, v61
	v_cvt_pk_bf16_f32 v145, v66, v67
	v_cvt_pk_bf16_f32 v147, v62, v63
	v_cvt_pk_bf16_f32 v148, v56, v57
	v_cvt_pk_bf16_f32 v150, v52, v53
	v_cvt_pk_bf16_f32 v149, v58, v59
	v_cvt_pk_bf16_f32 v151, v54, v55
	v_permlane16_swap_b32_e32 v144, v146
	v_permlane16_swap_b32_e32 v145, v147
	v_permlane16_swap_b32_e32 v148, v150
	v_permlane16_swap_b32_e32 v149, v151
	v_mov_b32_e32 v152, v144
	v_mov_b32_e32 v153, v145
	v_mov_b32_e32 v154, v146
	v_mov_b32_e32 v155, v147
	v_mov_b32_dpp v144, v148 row_ror:8 row_mask:0xf bank_mask:0xc
	v_mov_b32_dpp v145, v149 row_ror:8 row_mask:0xf bank_mask:0xc
	v_mov_b32_dpp v146, v150 row_ror:8 row_mask:0xf bank_mask:0xc
	v_mov_b32_dpp v147, v151 row_ror:8 row_mask:0xf bank_mask:0xc
	v_mov_b32_dpp v148, v152 row_ror:8 row_mask:0xf bank_mask:0x3
	v_mov_b32_dpp v149, v153 row_ror:8 row_mask:0xf bank_mask:0x3
	v_mov_b32_dpp v150, v154 row_ror:8 row_mask:0xf bank_mask:0x3
	v_mov_b32_dpp v151, v155 row_ror:8 row_mask:0xf bank_mask:0x3
	global_store_dwordx4 v[132:133], v[144:147], off nt
	global_store_dwordx4 v[134:135], v[148:151], off nt
	v_or_b32_e32 v172, 0x50, v2
	v_mad_i64_i32 v[168:169], s[26:27], s14, v172, 0
	v_lshl_add_u64 v[168:169], v[168:169], 1, s[12:13]
	v_lshl_add_u64 v[168:169], v[168:169], 0, v[0:1]
	v_lshl_add_u64 v[170:171], v[168:169], 0, s[18:19]
	v_cvt_pk_bf16_f32 v156, v48, v49
	v_cvt_pk_bf16_f32 v158, v44, v45
	v_cvt_pk_bf16_f32 v157, v50, v51
	v_cvt_pk_bf16_f32 v159, v46, v47
	v_cvt_pk_bf16_f32 v160, v40, v41
	v_cvt_pk_bf16_f32 v162, v36, v37
	v_cvt_pk_bf16_f32 v161, v42, v43
	v_cvt_pk_bf16_f32 v163, v38, v39
	v_permlane16_swap_b32_e32 v156, v158
	v_permlane16_swap_b32_e32 v157, v159
	v_permlane16_swap_b32_e32 v160, v162
	v_permlane16_swap_b32_e32 v161, v163
	v_mov_b32_e32 v164, v156
	v_mov_b32_e32 v165, v157
	v_mov_b32_e32 v166, v158
	v_mov_b32_e32 v167, v159
	v_mov_b32_dpp v156, v160 row_ror:8 row_mask:0xf bank_mask:0xc
	v_mov_b32_dpp v157, v161 row_ror:8 row_mask:0xf bank_mask:0xc
	v_mov_b32_dpp v158, v162 row_ror:8 row_mask:0xf bank_mask:0xc
	v_mov_b32_dpp v159, v163 row_ror:8 row_mask:0xf bank_mask:0xc
	v_mov_b32_dpp v160, v164 row_ror:8 row_mask:0xf bank_mask:0x3
	v_mov_b32_dpp v161, v165 row_ror:8 row_mask:0xf bank_mask:0x3
	v_mov_b32_dpp v162, v166 row_ror:8 row_mask:0xf bank_mask:0x3
	v_mov_b32_dpp v163, v167 row_ror:8 row_mask:0xf bank_mask:0x3
	global_store_dwordx4 v[168:169], v[156:159], off nt
	global_store_dwordx4 v[170:171], v[160:163], off nt
	v_or_b32_e32 v172, 0x60, v2
	v_mad_i64_i32 v[132:133], s[26:27], s14, v172, 0
	v_lshl_add_u64 v[132:133], v[132:133], 1, s[12:13]
	v_lshl_add_u64 v[132:133], v[132:133], 0, v[0:1]
	v_lshl_add_u64 v[134:135], v[132:133], 0, s[18:19]
	v_cvt_pk_bf16_f32 v144, v32, v33
	v_cvt_pk_bf16_f32 v146, v24, v25
	v_cvt_pk_bf16_f32 v145, v34, v35
	v_cvt_pk_bf16_f32 v147, v26, v27
	v_cvt_pk_bf16_f32 v148, v20, v21
	v_cvt_pk_bf16_f32 v150, v16, v17
	v_cvt_pk_bf16_f32 v149, v22, v23
	v_cvt_pk_bf16_f32 v151, v18, v19
	v_permlane16_swap_b32_e32 v144, v146
	v_permlane16_swap_b32_e32 v145, v147
	v_permlane16_swap_b32_e32 v148, v150
	v_permlane16_swap_b32_e32 v149, v151
	v_mov_b32_e32 v152, v144
	v_mov_b32_e32 v153, v145
	v_mov_b32_e32 v154, v146
	v_mov_b32_e32 v155, v147
	v_mov_b32_dpp v144, v148 row_ror:8 row_mask:0xf bank_mask:0xc
	v_mov_b32_dpp v145, v149 row_ror:8 row_mask:0xf bank_mask:0xc
	v_mov_b32_dpp v146, v150 row_ror:8 row_mask:0xf bank_mask:0xc
	v_mov_b32_dpp v147, v151 row_ror:8 row_mask:0xf bank_mask:0xc
	v_mov_b32_dpp v148, v152 row_ror:8 row_mask:0xf bank_mask:0x3
	v_mov_b32_dpp v149, v153 row_ror:8 row_mask:0xf bank_mask:0x3
	v_mov_b32_dpp v150, v154 row_ror:8 row_mask:0xf bank_mask:0x3
	v_mov_b32_dpp v151, v155 row_ror:8 row_mask:0xf bank_mask:0x3
	global_store_dwordx4 v[132:133], v[144:147], off nt
	global_store_dwordx4 v[134:135], v[148:151], off nt
	v_or_b32_e32 v172, 0x70, v2
	v_mad_i64_i32 v[168:169], s[26:27], s14, v172, 0
	v_lshl_add_u64 v[168:169], v[168:169], 1, s[12:13]
	v_lshl_add_u64 v[168:169], v[168:169], 0, v[0:1]
	v_lshl_add_u64 v[170:171], v[168:169], 0, s[18:19]
	v_cvt_pk_bf16_f32 v156, v12, v13
	v_cvt_pk_bf16_f32 v158, v8, v9
	v_cvt_pk_bf16_f32 v157, v14, v15
	v_cvt_pk_bf16_f32 v159, v10, v11
	v_cvt_pk_bf16_f32 v160, v4, v5
	v_cvt_pk_bf16_f32 v162, v28, v29
	v_cvt_pk_bf16_f32 v161, v6, v7
	v_cvt_pk_bf16_f32 v163, v30, v31
	v_permlane16_swap_b32_e32 v156, v158
	v_permlane16_swap_b32_e32 v157, v159
	v_permlane16_swap_b32_e32 v160, v162
	v_permlane16_swap_b32_e32 v161, v163
	v_mov_b32_e32 v164, v156
	v_mov_b32_e32 v165, v157
	v_mov_b32_e32 v166, v158
	v_mov_b32_e32 v167, v159
	v_mov_b32_dpp v156, v160 row_ror:8 row_mask:0xf bank_mask:0xc
	v_mov_b32_dpp v157, v161 row_ror:8 row_mask:0xf bank_mask:0xc
	v_mov_b32_dpp v158, v162 row_ror:8 row_mask:0xf bank_mask:0xc
	v_mov_b32_dpp v159, v163 row_ror:8 row_mask:0xf bank_mask:0xc
	v_mov_b32_dpp v160, v164 row_ror:8 row_mask:0xf bank_mask:0x3
	v_mov_b32_dpp v161, v165 row_ror:8 row_mask:0xf bank_mask:0x3
	v_mov_b32_dpp v162, v166 row_ror:8 row_mask:0xf bank_mask:0x3
	v_mov_b32_dpp v163, v167 row_ror:8 row_mask:0xf bank_mask:0x3
	global_store_dwordx4 v[168:169], v[156:159], off nt
	global_store_dwordx4 v[170:171], v[160:163], off nt
	s_add_i32 s23, s23, 1
	s_cmp_eq_u32 s23, s17
	s_cselect_b64 s[12:13], -1, 0
	s_mov_b32 s31, 0x18000
	s_branch .LBB0_708
